# out-proj/FF2 K-loop: nt hint on A-operand (mixed / H) LDS-DMA loads
# speedup vs baseline: 1.0123x; 1.0023x over previous
; #define PG8_STAGE(bufoff, gbase, voff) do { _Pragma("unroll") for (int _i = 0; _i < 2; ++_i) \
;         __builtin_amdgcn_global_load_lds((const unsigned*)((const char*)(gbase) + (voff)[_i]), (LAS unsigned*)(lds + (bufoff) + ldsw + _i * 8192), 16, 0, 0); } while (0)
; #define PG8_LDA(dst, b, h) do { _Pragma("unroll") for (int m = 0; m < 4; ++m) _Pragma("unroll") for (int k = 0; k < 2; ++k) dst[m][k] = *(const LAS bf16x8*)(lds + PG8_SA(b, h) + aoff + m * 2048 + k * 1024); } while (0)
; #define PG8_LDB(dst, b, h) do { _Pragma("unroll") for (int n = 0; n < 2; ++n) _Pragma("unroll") for (int k = 0; k < 2; ++k) dst[n][k] = *(const LAS bf16x8*)(lds + PG8_SB(b, h) + boff + n * 2048 + k * 1024); } while (0)
; #define PG8_WAIT_V(n) asm volatile("s_waitcnt vmcnt(" #n ")" ::: "memory")
; #define PG8_WAIT_L(n) asm volatile("s_waitcnt lgkmcnt(" #n ")" ::: "memory")
; #define PG8_BAR __builtin_amdgcn_s_barrier()
; #define PG8_SCHED __builtin_amdgcn_sched_barrier(0)
; template <class Epi>
; __device__ __forceinline__ void gemm_phase(LAS unsigned char* lds, const Gemm g, const StaticOrder& S, const Epi& E) {
;     ...
;         const bool has_next = S.next(ui + 1, nxt);
;         const char* nA = has_next ? (const char*)g.A + (size_t)nxt.pm * tstepA : cA; const char* nB = has_next ? (const char*)g.Bt + (size_t)nxt.pn * tstepB : cB;
;         for (int t = 0; t < nt; t += 2) {
;             const bool last = (t == nt - 2);
;             const char* a1 = cA + (size_t)(t + 1) * kstep;
;             const char* a2 = last ? nA : cA + (size_t)(t + 2) * kstep; const char* b2 = last ? nB : cB + (size_t)(t + 2) * kstep;
;             const char* a3 = a2 + kstep; const char* b3 = b2 + kstep;
;             PG8_LDB(B0, 0, 0); PG8_SCHED; PG8_LDA(At, 0, 0); PG8_STAGE(PG8_SA(1, 1), a1 + hstepA, voffA);
;             PG8_WAIT_L(8); PG8_BAR; PG8_WAIT_L(0); PG8_MMA(0, 0, At, B0); PG8_BAR; PG8_SCHED;
;             PG8_LDB(B1, 0, 1); PG8_STAGE(PG8_SB(0, 0), b2, voffB);
;             PG8_BAR; PG8_WAIT_L(0); PG8_MMA(0, 1, At, B1); PG8_BAR;
;             PG8_LDA(At, 0, 1); PG8_STAGE(PG8_SA(0, 0), a2, voffA);
;             PG8_BAR; PG8_WAIT_L(0); PG8_MMA(1, 0, At, B0); PG8_BAR; PG8_SCHED;
;             PG8_STAGE(PG8_SB(0, 1), b2 + hstepB, voffB);
;             PG8_WAIT_V(6); PG8_BAR; PG8_MMA(1, 1, At, B1); PG8_BAR;
.LBB0_186:
	s_add_u32 s4, s24, 0x4000
	s_addc_u32 s5, s25, 0
	s_add_u32 s50, s22, 0x8000
	s_addc_u32 s51, s23, 0
	s_mov_b32 s22, 0
	s_add_i32 s54, s22, 2
	s_add_u32 s23, s4, 0x4000
	s_addc_u32 s24, s5, 0
	s_cmp_eq_u32 s40, s22
	s_cselect_b32 s26, s6, s23
	s_cselect_b32 s27, s7, s24
	s_cselect_b32 s24, s20, s50
	s_cselect_b32 s25, s21, s51
	s_add_u32 s22, s26, 0x4000
	s_addc_u32 s23, s27, 0
	s_add_i32 m0, s33, 0xc000
	v_lshl_add_u64 v[186:187], s[4:5], 0, v[158:159]
	global_load_lds_dwordx4 v[186:187], off nt
	s_add_i32 m0, s33, 0xe000
	v_lshl_add_u64 v[186:187], s[4:5], 0, v[160:161]
	global_load_lds_dwordx4 v[186:187], off nt
	s_mov_b32 s55, 0x10000
	v_add_u32_e32 v140, s55, v207
	ds_read_b128 v[128:131], v140
	ds_read_b128 v[136:139], v140 offset:2048
	ds_read_b128 v[132:135], v140 offset:1024
	ds_read_b128 v[140:143], v140 offset:3072
	ds_read_b128 v[144:147], v209
	ds_read_b128 v[162:165], v209 offset:2048
	ds_read_b128 v[170:173], v209 offset:4096
	ds_read_b128 v[178:181], v209 offset:6144
	ds_read_b128 v[148:151], v209 offset:1024
	ds_read_b128 v[166:169], v209 offset:3072
	ds_read_b128 v[174:177], v209 offset:5120
	ds_read_b128 v[182:185], v209 offset:7168
	s_mov_b32 s58, 0x14000
	s_add_i32 s55, s55, s31
	v_add_u32_e32 v198, s58, v207
	ds_read_b128 v[186:189], v198
	ds_read_b128 v[194:197], v198 offset:2048
	ds_read_b128 v[190:193], v198 offset:1024
	ds_read_b128 v[198:201], v198 offset:3072
	s_waitcnt lgkmcnt(0)
	s_barrier
	v_mfma_f32_16x16x32_bf16 v[124:127], v[128:131], v[144:147], 0
	s_setprio 1
	v_mfma_f32_16x16x32_bf16 v[120:123], v[136:139], v[144:147], 0
	v_mfma_f32_16x16x32_bf16 v[116:119], v[128:131], v[162:165], 0
	v_mfma_f32_16x16x32_bf16 v[112:115], v[136:139], v[162:165], 0
	v_mfma_f32_16x16x32_bf16 v[108:111], v[128:131], v[170:173], 0
	v_mfma_f32_16x16x32_bf16 v[104:107], v[136:139], v[170:173], 0
	v_mfma_f32_16x16x32_bf16 v[100:103], v[128:131], v[178:181], 0
	v_mfma_f32_16x16x32_bf16 v[96:99], v[136:139], v[178:181], 0
	v_mfma_f32_16x16x32_bf16 v[124:127], v[132:135], v[148:151], v[124:127]
	v_mfma_f32_16x16x32_bf16 v[120:123], v[140:143], v[148:151], v[120:123]
	v_mfma_f32_16x16x32_bf16 v[116:119], v[132:135], v[166:169], v[116:119]
	v_mfma_f32_16x16x32_bf16 v[112:115], v[140:143], v[166:169], v[112:115]
	v_mfma_f32_16x16x32_bf16 v[108:111], v[132:135], v[174:177], v[108:111]
	v_mfma_f32_16x16x32_bf16 v[104:107], v[140:143], v[174:177], v[104:107]
	v_mfma_f32_16x16x32_bf16 v[100:103], v[132:135], v[182:185], v[100:103]
	v_mfma_f32_16x16x32_bf16 v[96:99], v[140:143], v[182:185], v[96:99]
	v_mfma_f32_16x16x32_bf16 v[92:95], v[186:189], v[144:147], 0
	v_mfma_f32_16x16x32_bf16 v[88:91], v[194:197], v[144:147], 0
	v_mfma_f32_16x16x32_bf16 v[84:87], v[186:189], v[162:165], 0
	v_mfma_f32_16x16x32_bf16 v[80:83], v[194:197], v[162:165], 0
	v_mfma_f32_16x16x32_bf16 v[76:79], v[186:189], v[170:173], 0
	v_mfma_f32_16x16x32_bf16 v[72:75], v[194:197], v[170:173], 0
	v_mfma_f32_16x16x32_bf16 v[68:71], v[186:189], v[178:181], 0
	v_mfma_f32_16x16x32_bf16 v[64:67], v[194:197], v[178:181], 0
	v_mfma_f32_16x16x32_bf16 v[92:95], v[190:193], v[148:151], v[92:95]
	v_mfma_f32_16x16x32_bf16 v[88:91], v[198:201], v[148:151], v[88:91]
	v_mfma_f32_16x16x32_bf16 v[84:87], v[190:193], v[166:169], v[84:87]
	v_mfma_f32_16x16x32_bf16 v[80:83], v[198:201], v[166:169], v[80:83]
	v_mfma_f32_16x16x32_bf16 v[76:79], v[190:193], v[174:177], v[76:79]
	v_mfma_f32_16x16x32_bf16 v[72:75], v[198:201], v[174:177], v[72:75]
	v_mfma_f32_16x16x32_bf16 v[68:71], v[190:193], v[182:185], v[68:71]
	s_setprio 0
	v_mfma_f32_16x16x32_bf16 v[64:67], v[198:201], v[182:185], v[64:67]
	s_barrier
	s_mov_b32 m0, s55
	v_lshl_add_u64 v[202:203], s[24:25], 0, v[152:153]
	global_load_lds_dwordx4 v[202:203], off
	s_add_i32 m0, s55, 0x2000
	v_lshl_add_u64 v[202:203], s[24:25], 0, v[156:157]
	global_load_lds_dwordx4 v[202:203], off
	s_mov_b32 m0, s33
	v_lshl_add_u64 v[202:203], s[26:27], 0, v[152:153]
	global_load_lds_dwordx4 v[202:203], off nt
	s_mov_b32 m0, s34
	v_lshl_add_u64 v[202:203], s[26:27], 0, v[156:157]
	global_load_lds_dwordx4 v[202:203], off nt
	s_add_u32 s56, s24, s52
	s_addc_u32 s57, s25, 0
	s_add_i32 s55, s58, s31
	s_mov_b32 m0, s55
	v_lshl_add_u64 v[202:203], s[56:57], 0, v[152:153]
	global_load_lds_dwordx4 v[202:203], off
	s_add_i32 m0, s55, 0x2000
	v_lshl_add_u64 v[202:203], s[56:57], 0, v[156:157]
	global_load_lds_dwordx4 v[202:203], off
	ds_read_b128 v[144:147], v209 offset:16384
	ds_read_b128 v[162:165], v209 offset:18432
	ds_read_b128 v[170:173], v209 offset:20480
	ds_read_b128 v[178:181], v209 offset:22528
	ds_read_b128 v[148:151], v209 offset:17408
	ds_read_b128 v[166:169], v209 offset:19456
	ds_read_b128 v[174:177], v209 offset:21504
	ds_read_b128 v[182:185], v209 offset:23552
	s_waitcnt vmcnt(6)
	s_waitcnt lgkmcnt(0)
	s_barrier
; #define PG8_STAGE(bufoff, gbase, voff) do { _Pragma("unroll") for (int _i = 0; _i < 2; ++_i) \
;         __builtin_amdgcn_global_load_lds((const unsigned*)((const char*)(gbase) + (voff)[_i]), (LAS unsigned*)(lds + (bufoff) + ldsw + _i * 8192), 16, 0, 0); } while (0)
; #define PG8_LDA(dst, b, h) do { _Pragma("unroll") for (int m = 0; m < 4; ++m) _Pragma("unroll") for (int k = 0; k < 2; ++k) dst[m][k] = *(const LAS bf16x8*)(lds + PG8_SA(b, h) + aoff + m * 2048 + k * 1024); } while (0)
; #define PG8_LDB(dst, b, h) do { _Pragma("unroll") for (int n = 0; n < 2; ++n) _Pragma("unroll") for (int k = 0; k < 2; ++k) dst[n][k] = *(const LAS bf16x8*)(lds + PG8_SB(b, h) + boff + n * 2048 + k * 1024); } while (0)
; #define PG8_MMA(ai, bj, At, Bt) do { __builtin_amdgcn_s_setprio(1); _Pragma("unroll") for (int m = 0; m < 4; ++m) _Pragma("unroll") for (int n = 0; n < 2; ++n) _Pragma("unroll") for (int k = 0; k < 2; ++k) \
;         acc[ai][bj][m][n] = __builtin_amdgcn_mfma_f32_16x16x32_bf16(Bt[n][k], At[m][k], acc[ai][bj][m][n], 0, 0, 0); __builtin_amdgcn_s_setprio(0); } while (0)
; #define PG8_WAIT_V(n) asm volatile("s_waitcnt vmcnt(" #n ")" ::: "memory")
; #define PG8_WAIT_L(n) asm volatile("s_waitcnt lgkmcnt(" #n ")" ::: "memory")
; #define PG8_BAR __builtin_amdgcn_s_barrier()
; #define PG8_SCHED __builtin_amdgcn_sched_barrier(0)
; template <class Epi>
; __device__ __forceinline__ void gemm_phase(LAS unsigned char* lds, const Gemm g, const StaticOrder& S, const Epi& E) {
;     ...
;             PG8_STAGE(PG8_SB(0, 1), b2 + hstepB, voffB);
;             PG8_WAIT_V(6); PG8_BAR; PG8_MMA(1, 1, At, B1); PG8_BAR;
;             PG8_LDB(B0, 1, 0); PG8_SCHED; PG8_LDA(At, 1, 0); PG8_STAGE(PG8_SA(0, 1), a2 + hstepA, voffA);
;             PG8_WAIT_L(8); PG8_BAR; PG8_WAIT_L(0); PG8_MMA(0, 0, At, B0); PG8_BAR; PG8_SCHED;
;             PG8_LDB(B1, 1, 1); PG8_STAGE(PG8_SB(1, 0), b3, voffB);
;             PG8_BAR; PG8_WAIT_L(0); PG8_MMA(0, 1, At, B1); PG8_BAR;
	v_mfma_f32_16x16x32_bf16 v[60:63], v[128:131], v[144:147], 0
	s_setprio 1
	v_mfma_f32_16x16x32_bf16 v[56:59], v[136:139], v[144:147], 0
	v_mfma_f32_16x16x32_bf16 v[52:55], v[128:131], v[162:165], 0
	v_mfma_f32_16x16x32_bf16 v[48:51], v[136:139], v[162:165], 0
	v_mfma_f32_16x16x32_bf16 v[44:47], v[128:131], v[170:173], 0
	v_mfma_f32_16x16x32_bf16 v[40:43], v[136:139], v[170:173], 0
	v_mfma_f32_16x16x32_bf16 v[36:39], v[128:131], v[178:181], 0
	v_mfma_f32_16x16x32_bf16 v[32:35], v[136:139], v[178:181], 0
	v_mfma_f32_16x16x32_bf16 v[60:63], v[132:135], v[148:151], v[60:63]
	v_mfma_f32_16x16x32_bf16 v[56:59], v[140:143], v[148:151], v[56:59]
	v_mfma_f32_16x16x32_bf16 v[52:55], v[132:135], v[166:169], v[52:55]
	v_mfma_f32_16x16x32_bf16 v[48:51], v[140:143], v[166:169], v[48:51]
	v_mfma_f32_16x16x32_bf16 v[44:47], v[132:135], v[174:177], v[44:47]
	v_mfma_f32_16x16x32_bf16 v[40:43], v[140:143], v[174:177], v[40:43]
	v_mfma_f32_16x16x32_bf16 v[36:39], v[132:135], v[182:185], v[36:39]
	v_mfma_f32_16x16x32_bf16 v[32:35], v[140:143], v[182:185], v[32:35]
	v_mfma_f32_16x16x32_bf16 v[28:31], v[186:189], v[144:147], 0
	v_mfma_f32_16x16x32_bf16 v[24:27], v[194:197], v[144:147], 0
	s_add_i32 s55, 0, 0x18000
	v_add_u32_e32 v140, s55, v207
	v_mfma_f32_16x16x32_bf16 v[20:23], v[186:189], v[162:165], 0
	v_mfma_f32_16x16x32_bf16 v[16:19], v[194:197], v[162:165], 0
	v_mfma_f32_16x16x32_bf16 v[12:15], v[186:189], v[170:173], 0
	v_mfma_f32_16x16x32_bf16 v[8:11], v[194:197], v[170:173], 0
	v_mfma_f32_16x16x32_bf16 v[4:7], v[186:189], v[178:181], 0
	v_mfma_f32_16x16x32_bf16 v[0:3], v[194:197], v[178:181], 0
	v_mfma_f32_16x16x32_bf16 v[28:31], v[190:193], v[148:151], v[28:31]
	v_mfma_f32_16x16x32_bf16 v[24:27], v[198:201], v[148:151], v[24:27]
	v_mfma_f32_16x16x32_bf16 v[20:23], v[190:193], v[166:169], v[20:23]
	v_mfma_f32_16x16x32_bf16 v[16:19], v[198:201], v[166:169], v[16:19]
	v_mfma_f32_16x16x32_bf16 v[12:15], v[190:193], v[174:177], v[12:15]
	v_mfma_f32_16x16x32_bf16 v[8:11], v[198:201], v[174:177], v[8:11]
	v_mfma_f32_16x16x32_bf16 v[4:7], v[190:193], v[182:185], v[4:7]
	s_setprio 0
	v_mfma_f32_16x16x32_bf16 v[0:3], v[198:201], v[182:185], v[0:3]
	s_barrier
	s_add_u32 s26, s26, s52
	s_addc_u32 s27, s27, 0
	s_mov_b32 m0, s35
	v_lshl_add_u64 v[186:187], s[26:27], 0, v[152:153]
	global_load_lds_dwordx4 v[186:187], off nt
	s_mov_b32 m0, s36
	v_lshl_add_u64 v[186:187], s[26:27], 0, v[156:157]
	global_load_lds_dwordx4 v[186:187], off nt
	ds_read_b128 v[128:131], v140
	ds_read_b128 v[136:139], v140 offset:2048
	ds_read_b128 v[132:135], v140 offset:1024
	ds_read_b128 v[140:143], v140 offset:3072
	ds_read_b128 v[144:147], v209 offset:32768
	ds_read_b128 v[162:165], v209 offset:34816
	ds_read_b128 v[170:173], v209 offset:36864
	ds_read_b128 v[178:181], v209 offset:38912
	ds_read_b128 v[148:151], v209 offset:33792
	ds_read_b128 v[166:169], v209 offset:35840
	ds_read_b128 v[174:177], v209 offset:37888
	ds_read_b128 v[182:185], v209 offset:39936
	s_mov_b32 s26, 0x1c000
	s_add_u32 s24, s24, 0x4000
	s_addc_u32 s25, s25, 0
	s_add_i32 s27, s55, s31
	v_add_u32_e32 v198, s26, v207
	ds_read_b128 v[186:189], v198
	ds_read_b128 v[194:197], v198 offset:2048
	ds_read_b128 v[190:193], v198 offset:1024
	ds_read_b128 v[198:201], v198 offset:3072
	s_waitcnt lgkmcnt(0)
	s_barrier
	v_mfma_f32_16x16x32_bf16 v[124:127], v[128:131], v[144:147], v[124:127]
	s_setprio 1
	v_mfma_f32_16x16x32_bf16 v[120:123], v[136:139], v[144:147], v[120:123]
	v_mfma_f32_16x16x32_bf16 v[116:119], v[128:131], v[162:165], v[116:119]
	v_mfma_f32_16x16x32_bf16 v[112:115], v[136:139], v[162:165], v[112:115]
	v_mfma_f32_16x16x32_bf16 v[108:111], v[128:131], v[170:173], v[108:111]
	v_mfma_f32_16x16x32_bf16 v[104:107], v[136:139], v[170:173], v[104:107]
	v_mfma_f32_16x16x32_bf16 v[100:103], v[128:131], v[178:181], v[100:103]
	v_mfma_f32_16x16x32_bf16 v[96:99], v[136:139], v[178:181], v[96:99]
	v_mfma_f32_16x16x32_bf16 v[124:127], v[132:135], v[148:151], v[124:127]
	v_mfma_f32_16x16x32_bf16 v[120:123], v[140:143], v[148:151], v[120:123]
	v_mfma_f32_16x16x32_bf16 v[116:119], v[132:135], v[166:169], v[116:119]
	v_mfma_f32_16x16x32_bf16 v[112:115], v[140:143], v[166:169], v[112:115]
	v_mfma_f32_16x16x32_bf16 v[108:111], v[132:135], v[174:177], v[108:111]
	v_mfma_f32_16x16x32_bf16 v[104:107], v[140:143], v[174:177], v[104:107]
	v_mfma_f32_16x16x32_bf16 v[100:103], v[132:135], v[182:185], v[100:103]
	v_mfma_f32_16x16x32_bf16 v[96:99], v[140:143], v[182:185], v[96:99]
	v_mfma_f32_16x16x32_bf16 v[92:95], v[186:189], v[144:147], v[92:95]
	v_mfma_f32_16x16x32_bf16 v[88:91], v[194:197], v[144:147], v[88:91]
	v_mfma_f32_16x16x32_bf16 v[84:87], v[186:189], v[162:165], v[84:87]
	v_mfma_f32_16x16x32_bf16 v[80:83], v[194:197], v[162:165], v[80:83]
	v_mfma_f32_16x16x32_bf16 v[76:79], v[186:189], v[170:173], v[76:79]
	v_mfma_f32_16x16x32_bf16 v[72:75], v[194:197], v[170:173], v[72:75]
	v_mfma_f32_16x16x32_bf16 v[68:71], v[186:189], v[178:181], v[68:71]
	v_mfma_f32_16x16x32_bf16 v[64:67], v[194:197], v[178:181], v[64:67]
	v_mfma_f32_16x16x32_bf16 v[92:95], v[190:193], v[148:151], v[92:95]
	v_mfma_f32_16x16x32_bf16 v[88:91], v[198:201], v[148:151], v[88:91]
	v_mfma_f32_16x16x32_bf16 v[84:87], v[190:193], v[166:169], v[84:87]
	v_mfma_f32_16x16x32_bf16 v[80:83], v[198:201], v[166:169], v[80:83]
	v_mfma_f32_16x16x32_bf16 v[76:79], v[190:193], v[174:177], v[76:79]
	v_mfma_f32_16x16x32_bf16 v[72:75], v[198:201], v[174:177], v[72:75]
	v_mfma_f32_16x16x32_bf16 v[68:71], v[190:193], v[182:185], v[68:71]
	s_setprio 0
	v_mfma_f32_16x16x32_bf16 v[64:67], v[198:201], v[182:185], v[64:67]
	s_barrier
; #define PG8_STAGE(bufoff, gbase, voff) do { _Pragma("unroll") for (int _i = 0; _i < 2; ++_i) \
;         __builtin_amdgcn_global_load_lds((const unsigned*)((const char*)(gbase) + (voff)[_i]), (LAS unsigned*)(lds + (bufoff) + ldsw + _i * 8192), 16, 0, 0); } while (0)
; #define PG8_LDA(dst, b, h) do { _Pragma("unroll") for (int m = 0; m < 4; ++m) _Pragma("unroll") for (int k = 0; k < 2; ++k) dst[m][k] = *(const LAS bf16x8*)(lds + PG8_SA(b, h) + aoff + m * 2048 + k * 1024); } while (0)
; #define PG8_LDB(dst, b, h) do { _Pragma("unroll") for (int n = 0; n < 2; ++n) _Pragma("unroll") for (int k = 0; k < 2; ++k) dst[n][k] = *(const LAS bf16x8*)(lds + PG8_SB(b, h) + boff + n * 2048 + k * 1024); } while (0)
; #define PG8_MMA(ai, bj, At, Bt) do { __builtin_amdgcn_s_setprio(1); _Pragma("unroll") for (int m = 0; m < 4; ++m) _Pragma("unroll") for (int n = 0; n < 2; ++n) _Pragma("unroll") for (int k = 0; k < 2; ++k) \
;         acc[ai][bj][m][n] = __builtin_amdgcn_mfma_f32_16x16x32_bf16(Bt[n][k], At[m][k], acc[ai][bj][m][n], 0, 0, 0); __builtin_amdgcn_s_setprio(0); } while (0)
; #define PG8_WAIT_V(n) asm volatile("s_waitcnt vmcnt(" #n ")" ::: "memory")
; #define PG8_WAIT_L(n) asm volatile("s_waitcnt lgkmcnt(" #n ")" ::: "memory")
; #define PG8_BAR __builtin_amdgcn_s_barrier()
; #define PG8_SCHED __builtin_amdgcn_sched_barrier(0)
; template <class Epi>
; __device__ __forceinline__ void gemm_phase(LAS unsigned char* lds, const Gemm g, const StaticOrder& S, const Epi& E) {
;     ...
;             PG8_LDB(B0, 0, 0); PG8_SCHED; PG8_LDA(At, 0, 0); PG8_STAGE(PG8_SA(1, 1), a1 + hstepA, voffA);
;     ...
;             PG8_LDA(At, 1, 1); PG8_STAGE(PG8_SA(1, 0), a3, voffA);
;             PG8_BAR; PG8_WAIT_L(0); PG8_MMA(1, 0, At, B0); PG8_BAR; PG8_SCHED;
;             PG8_STAGE(PG8_SB(1, 1), b3 + hstepB, voffB);
;             PG8_WAIT_V(6); PG8_BAR; PG8_MMA(1, 1, At, B1); PG8_BAR;
	s_mov_b32 m0, s27
	v_lshl_add_u64 v[202:203], s[24:25], 0, v[152:153]
	global_load_lds_dwordx4 v[202:203], off
	s_add_i32 m0, s27, 0x2000
	v_lshl_add_u64 v[202:203], s[24:25], 0, v[156:157]
	global_load_lds_dwordx4 v[202:203], off
	s_mov_b32 m0, s38
	v_lshl_add_u64 v[202:203], s[22:23], 0, v[152:153]
	global_load_lds_dwordx4 v[202:203], off nt
	s_mov_b32 m0, s39
	v_lshl_add_u64 v[202:203], s[22:23], 0, v[156:157]
	global_load_lds_dwordx4 v[202:203], off nt
	s_add_u32 s22, s24, s52
	s_addc_u32 s23, s25, 0
	s_add_i32 s24, s26, s31
	s_mov_b32 m0, s24
	v_lshl_add_u64 v[202:203], s[22:23], 0, v[152:153]
	global_load_lds_dwordx4 v[202:203], off
	s_add_i32 m0, s24, 0x2000
	v_lshl_add_u64 v[202:203], s[22:23], 0, v[156:157]
	global_load_lds_dwordx4 v[202:203], off
	ds_read_b128 v[144:147], v209 offset:49152
	ds_read_b128 v[162:165], v209 offset:51200
	ds_read_b128 v[170:173], v209 offset:53248
	ds_read_b128 v[178:181], v209 offset:55296
	ds_read_b128 v[148:151], v209 offset:50176
	ds_read_b128 v[166:169], v209 offset:52224
	ds_read_b128 v[174:177], v209 offset:54272
	ds_read_b128 v[182:185], v209 offset:56320
	s_waitcnt vmcnt(6)
	s_waitcnt lgkmcnt(0)
	s_barrier
	v_mfma_f32_16x16x32_bf16 v[60:63], v[128:131], v[144:147], v[60:63]
	s_setprio 1
	v_mfma_f32_16x16x32_bf16 v[56:59], v[136:139], v[144:147], v[56:59]
	v_mfma_f32_16x16x32_bf16 v[52:55], v[128:131], v[162:165], v[52:55]
	v_mfma_f32_16x16x32_bf16 v[48:51], v[136:139], v[162:165], v[48:51]
	v_mfma_f32_16x16x32_bf16 v[44:47], v[128:131], v[170:173], v[44:47]
	v_mfma_f32_16x16x32_bf16 v[40:43], v[136:139], v[170:173], v[40:43]
	v_mfma_f32_16x16x32_bf16 v[36:39], v[128:131], v[178:181], v[36:39]
	v_mfma_f32_16x16x32_bf16 v[32:35], v[136:139], v[178:181], v[32:35]
	v_mfma_f32_16x16x32_bf16 v[60:63], v[132:135], v[148:151], v[60:63]
	v_mfma_f32_16x16x32_bf16 v[56:59], v[140:143], v[148:151], v[56:59]
	v_mfma_f32_16x16x32_bf16 v[52:55], v[132:135], v[166:169], v[52:55]
	v_mfma_f32_16x16x32_bf16 v[48:51], v[140:143], v[166:169], v[48:51]
	v_mfma_f32_16x16x32_bf16 v[44:47], v[132:135], v[174:177], v[44:47]
	v_mfma_f32_16x16x32_bf16 v[40:43], v[140:143], v[174:177], v[40:43]
	v_mfma_f32_16x16x32_bf16 v[36:39], v[132:135], v[182:185], v[36:39]
	v_mfma_f32_16x16x32_bf16 v[32:35], v[140:143], v[182:185], v[32:35]
	v_mfma_f32_16x16x32_bf16 v[28:31], v[186:189], v[144:147], v[28:31]
	v_mfma_f32_16x16x32_bf16 v[24:27], v[194:197], v[144:147], v[24:27]
	s_add_u32 s4, s4, 0x8000
	s_addc_u32 s5, s5, 0
	s_add_u32 s50, s50, 0x8000
	s_addc_u32 s51, s51, 0
	v_mfma_f32_16x16x32_bf16 v[20:23], v[186:189], v[162:165], v[20:23]
	v_mfma_f32_16x16x32_bf16 v[16:19], v[194:197], v[162:165], v[16:19]
	v_mfma_f32_16x16x32_bf16 v[12:15], v[186:189], v[170:173], v[12:15]
	v_mfma_f32_16x16x32_bf16 v[8:11], v[194:197], v[170:173], v[8:11]
	v_mfma_f32_16x16x32_bf16 v[4:7], v[186:189], v[178:181], v[4:7]
	v_mfma_f32_16x16x32_bf16 v[0:3], v[194:197], v[178:181], v[0:3]
	v_mfma_f32_16x16x32_bf16 v[28:31], v[190:193], v[148:151], v[28:31]
	v_mfma_f32_16x16x32_bf16 v[24:27], v[198:201], v[148:151], v[24:27]
	v_mfma_f32_16x16x32_bf16 v[20:23], v[190:193], v[166:169], v[20:23]
	v_mfma_f32_16x16x32_bf16 v[16:19], v[198:201], v[166:169], v[16:19]
	v_mfma_f32_16x16x32_bf16 v[12:15], v[190:193], v[174:177], v[12:15]
	v_mfma_f32_16x16x32_bf16 v[8:11], v[198:201], v[174:177], v[8:11]
	v_mfma_f32_16x16x32_bf16 v[4:7], v[190:193], v[182:185], v[4:7]
	s_cmp_ge_u32 s54, s28
	s_mov_b32 s22, s54
	s_setprio 0
	v_mfma_f32_16x16x32_bf16 v[0:3], v[198:201], v[182:185], v[0:3]
	s_barrier
	s_cbranch_scc0 .LBB0_187
	s_branch .Lpeel_done_187
.LBB0_187:
	s_add_i32 s54, s22, 2
	s_add_u32 s23, s4, 0x4000
	s_addc_u32 s24, s5, 0
	s_cmp_eq_u32 s40, s22
	s_cselect_b32 s26, s6, s23
	s_cselect_b32 s27, s7, s24
	s_cselect_b32 s24, s20, s50
	s_cselect_b32 s25, s21, s51
	s_add_u32 s22, s26, 0x4000
	s_addc_u32 s23, s27, 0
	s_add_i32 m0, s33, 0xc000
	v_lshl_add_u64 v[186:187], s[4:5], 0, v[158:159]
	global_load_lds_dwordx4 v[186:187], off nt
	s_add_i32 m0, s33, 0xe000
	v_lshl_add_u64 v[186:187], s[4:5], 0, v[160:161]
	global_load_lds_dwordx4 v[186:187], off nt
	s_mov_b32 s55, 0x10000
	v_add_u32_e32 v140, s55, v207
	ds_read_b128 v[128:131], v140
	ds_read_b128 v[136:139], v140 offset:2048
	ds_read_b128 v[132:135], v140 offset:1024
	ds_read_b128 v[140:143], v140 offset:3072
	ds_read_b128 v[144:147], v209
	ds_read_b128 v[162:165], v209 offset:2048
	ds_read_b128 v[170:173], v209 offset:4096
	ds_read_b128 v[178:181], v209 offset:6144
	ds_read_b128 v[148:151], v209 offset:1024
	ds_read_b128 v[166:169], v209 offset:3072
	ds_read_b128 v[174:177], v209 offset:5120
	ds_read_b128 v[182:185], v209 offset:7168
	s_mov_b32 s58, 0x14000
	s_add_i32 s55, s55, s31
	v_add_u32_e32 v198, s58, v207
	ds_read_b128 v[186:189], v198
	ds_read_b128 v[194:197], v198 offset:2048
	ds_read_b128 v[190:193], v198 offset:1024
	ds_read_b128 v[198:201], v198 offset:3072
	s_waitcnt lgkmcnt(0)
	s_barrier
; #define PG8_STAGE(bufoff, gbase, voff) do { _Pragma("unroll") for (int _i = 0; _i < 2; ++_i) \
;         __builtin_amdgcn_global_load_lds((const unsigned*)((const char*)(gbase) + (voff)[_i]), (LAS unsigned*)(lds + (bufoff) + ldsw + _i * 8192), 16, 0, 0); } while (0)
; #define PG8_LDA(dst, b, h) do { _Pragma("unroll") for (int m = 0; m < 4; ++m) _Pragma("unroll") for (int k = 0; k < 2; ++k) dst[m][k] = *(const LAS bf16x8*)(lds + PG8_SA(b, h) + aoff + m * 2048 + k * 1024); } while (0)
; #define PG8_LDB(dst, b, h) do { _Pragma("unroll") for (int n = 0; n < 2; ++n) _Pragma("unroll") for (int k = 0; k < 2; ++k) dst[n][k] = *(const LAS bf16x8*)(lds + PG8_SB(b, h) + boff + n * 2048 + k * 1024); } while (0)
; #define PG8_MMA(ai, bj, At, Bt) do { __builtin_amdgcn_s_setprio(1); _Pragma("unroll") for (int m = 0; m < 4; ++m) _Pragma("unroll") for (int n = 0; n < 2; ++n) _Pragma("unroll") for (int k = 0; k < 2; ++k) \
;         acc[ai][bj][m][n] = __builtin_amdgcn_mfma_f32_16x16x32_bf16(Bt[n][k], At[m][k], acc[ai][bj][m][n], 0, 0, 0); __builtin_amdgcn_s_setprio(0); } while (0)
; #define PG8_WAIT_V(n) asm volatile("s_waitcnt vmcnt(" #n ")" ::: "memory")
; #define PG8_WAIT_L(n) asm volatile("s_waitcnt lgkmcnt(" #n ")" ::: "memory")
; #define PG8_BAR __builtin_amdgcn_s_barrier()
; #define PG8_SCHED __builtin_amdgcn_sched_barrier(0)
; template <class Epi>
; __device__ __forceinline__ void gemm_phase(LAS unsigned char* lds, const Gemm g, const StaticOrder& S, const Epi& E) {
;     ...
;             PG8_WAIT_L(8); PG8_BAR; PG8_WAIT_L(0); PG8_MMA(0, 0, At, B0); PG8_BAR; PG8_SCHED;
;             PG8_LDB(B1, 0, 1); PG8_STAGE(PG8_SB(0, 0), b2, voffB);
;             PG8_BAR; PG8_WAIT_L(0); PG8_MMA(0, 1, At, B1); PG8_BAR;
;             PG8_LDA(At, 0, 1); PG8_STAGE(PG8_SA(0, 0), a2, voffA);
;             PG8_BAR; PG8_WAIT_L(0); PG8_MMA(1, 0, At, B0); PG8_BAR; PG8_SCHED;
;             PG8_STAGE(PG8_SB(0, 1), b2 + hstepB, voffB);
;             PG8_WAIT_V(6); PG8_BAR; PG8_MMA(1, 1, At, B1); PG8_BAR;
	v_mfma_f32_16x16x32_bf16 v[124:127], v[128:131], v[144:147], v[124:127]
	s_setprio 1
	v_mfma_f32_16x16x32_bf16 v[120:123], v[136:139], v[144:147], v[120:123]
	v_mfma_f32_16x16x32_bf16 v[116:119], v[128:131], v[162:165], v[116:119]
	v_mfma_f32_16x16x32_bf16 v[112:115], v[136:139], v[162:165], v[112:115]
	v_mfma_f32_16x16x32_bf16 v[108:111], v[128:131], v[170:173], v[108:111]
	v_mfma_f32_16x16x32_bf16 v[104:107], v[136:139], v[170:173], v[104:107]
	v_mfma_f32_16x16x32_bf16 v[100:103], v[128:131], v[178:181], v[100:103]
	v_mfma_f32_16x16x32_bf16 v[96:99], v[136:139], v[178:181], v[96:99]
	v_mfma_f32_16x16x32_bf16 v[124:127], v[132:135], v[148:151], v[124:127]
	v_mfma_f32_16x16x32_bf16 v[120:123], v[140:143], v[148:151], v[120:123]
	v_mfma_f32_16x16x32_bf16 v[116:119], v[132:135], v[166:169], v[116:119]
	v_mfma_f32_16x16x32_bf16 v[112:115], v[140:143], v[166:169], v[112:115]
	v_mfma_f32_16x16x32_bf16 v[108:111], v[132:135], v[174:177], v[108:111]
	v_mfma_f32_16x16x32_bf16 v[104:107], v[140:143], v[174:177], v[104:107]
	v_mfma_f32_16x16x32_bf16 v[100:103], v[132:135], v[182:185], v[100:103]
	v_mfma_f32_16x16x32_bf16 v[96:99], v[140:143], v[182:185], v[96:99]
	v_mfma_f32_16x16x32_bf16 v[92:95], v[186:189], v[144:147], v[92:95]
	v_mfma_f32_16x16x32_bf16 v[88:91], v[194:197], v[144:147], v[88:91]
	v_mfma_f32_16x16x32_bf16 v[84:87], v[186:189], v[162:165], v[84:87]
	v_mfma_f32_16x16x32_bf16 v[80:83], v[194:197], v[162:165], v[80:83]
	v_mfma_f32_16x16x32_bf16 v[76:79], v[186:189], v[170:173], v[76:79]
	v_mfma_f32_16x16x32_bf16 v[72:75], v[194:197], v[170:173], v[72:75]
	v_mfma_f32_16x16x32_bf16 v[68:71], v[186:189], v[178:181], v[68:71]
	v_mfma_f32_16x16x32_bf16 v[64:67], v[194:197], v[178:181], v[64:67]
	v_mfma_f32_16x16x32_bf16 v[92:95], v[190:193], v[148:151], v[92:95]
	v_mfma_f32_16x16x32_bf16 v[88:91], v[198:201], v[148:151], v[88:91]
	v_mfma_f32_16x16x32_bf16 v[84:87], v[190:193], v[166:169], v[84:87]
	v_mfma_f32_16x16x32_bf16 v[80:83], v[198:201], v[166:169], v[80:83]
	v_mfma_f32_16x16x32_bf16 v[76:79], v[190:193], v[174:177], v[76:79]
	v_mfma_f32_16x16x32_bf16 v[72:75], v[198:201], v[174:177], v[72:75]
	v_mfma_f32_16x16x32_bf16 v[68:71], v[190:193], v[182:185], v[68:71]
	s_setprio 0
	v_mfma_f32_16x16x32_bf16 v[64:67], v[198:201], v[182:185], v[64:67]
	s_barrier
	s_mov_b32 m0, s55
	v_lshl_add_u64 v[202:203], s[24:25], 0, v[152:153]
	global_load_lds_dwordx4 v[202:203], off
	s_add_i32 m0, s55, 0x2000
	v_lshl_add_u64 v[202:203], s[24:25], 0, v[156:157]
	global_load_lds_dwordx4 v[202:203], off
	s_mov_b32 m0, s33
	v_lshl_add_u64 v[202:203], s[26:27], 0, v[152:153]
	global_load_lds_dwordx4 v[202:203], off nt
	s_mov_b32 m0, s34
	v_lshl_add_u64 v[202:203], s[26:27], 0, v[156:157]
	global_load_lds_dwordx4 v[202:203], off nt
	s_add_u32 s56, s24, s52
	s_addc_u32 s57, s25, 0
	s_add_i32 s55, s58, s31
	s_mov_b32 m0, s55
	v_lshl_add_u64 v[202:203], s[56:57], 0, v[152:153]
	global_load_lds_dwordx4 v[202:203], off
	s_add_i32 m0, s55, 0x2000
	v_lshl_add_u64 v[202:203], s[56:57], 0, v[156:157]
	global_load_lds_dwordx4 v[202:203], off
	ds_read_b128 v[144:147], v209 offset:16384
	ds_read_b128 v[162:165], v209 offset:18432
	ds_read_b128 v[170:173], v209 offset:20480
	ds_read_b128 v[178:181], v209 offset:22528
	ds_read_b128 v[148:151], v209 offset:17408
	ds_read_b128 v[166:169], v209 offset:19456
	ds_read_b128 v[174:177], v209 offset:21504
	ds_read_b128 v[182:185], v209 offset:23552
	s_waitcnt vmcnt(6)
	s_waitcnt lgkmcnt(0)
	s_barrier
	v_mfma_f32_16x16x32_bf16 v[60:63], v[128:131], v[144:147], v[60:63]
	s_setprio 1
	v_mfma_f32_16x16x32_bf16 v[56:59], v[136:139], v[144:147], v[56:59]
	v_mfma_f32_16x16x32_bf16 v[52:55], v[128:131], v[162:165], v[52:55]
	v_mfma_f32_16x16x32_bf16 v[48:51], v[136:139], v[162:165], v[48:51]
	v_mfma_f32_16x16x32_bf16 v[44:47], v[128:131], v[170:173], v[44:47]
	v_mfma_f32_16x16x32_bf16 v[40:43], v[136:139], v[170:173], v[40:43]
	v_mfma_f32_16x16x32_bf16 v[36:39], v[128:131], v[178:181], v[36:39]
	v_mfma_f32_16x16x32_bf16 v[32:35], v[136:139], v[178:181], v[32:35]
	v_mfma_f32_16x16x32_bf16 v[60:63], v[132:135], v[148:151], v[60:63]
	v_mfma_f32_16x16x32_bf16 v[56:59], v[140:143], v[148:151], v[56:59]
	v_mfma_f32_16x16x32_bf16 v[52:55], v[132:135], v[166:169], v[52:55]
	v_mfma_f32_16x16x32_bf16 v[48:51], v[140:143], v[166:169], v[48:51]
	v_mfma_f32_16x16x32_bf16 v[44:47], v[132:135], v[174:177], v[44:47]
	v_mfma_f32_16x16x32_bf16 v[40:43], v[140:143], v[174:177], v[40:43]
	v_mfma_f32_16x16x32_bf16 v[36:39], v[132:135], v[182:185], v[36:39]
	v_mfma_f32_16x16x32_bf16 v[32:35], v[140:143], v[182:185], v[32:35]
	v_mfma_f32_16x16x32_bf16 v[28:31], v[186:189], v[144:147], v[28:31]
	v_mfma_f32_16x16x32_bf16 v[24:27], v[194:197], v[144:147], v[24:27]
	s_add_i32 s55, 0, 0x18000
	v_add_u32_e32 v140, s55, v207
	v_mfma_f32_16x16x32_bf16 v[20:23], v[186:189], v[162:165], v[20:23]
	v_mfma_f32_16x16x32_bf16 v[16:19], v[194:197], v[162:165], v[16:19]
	v_mfma_f32_16x16x32_bf16 v[12:15], v[186:189], v[170:173], v[12:15]
	v_mfma_f32_16x16x32_bf16 v[8:11], v[194:197], v[170:173], v[8:11]
	v_mfma_f32_16x16x32_bf16 v[4:7], v[186:189], v[178:181], v[4:7]
	v_mfma_f32_16x16x32_bf16 v[0:3], v[194:197], v[178:181], v[0:3]
	v_mfma_f32_16x16x32_bf16 v[28:31], v[190:193], v[148:151], v[28:31]
	v_mfma_f32_16x16x32_bf16 v[24:27], v[198:201], v[148:151], v[24:27]
	v_mfma_f32_16x16x32_bf16 v[20:23], v[190:193], v[166:169], v[20:23]
	v_mfma_f32_16x16x32_bf16 v[16:19], v[198:201], v[166:169], v[16:19]
	v_mfma_f32_16x16x32_bf16 v[12:15], v[190:193], v[174:177], v[12:15]
	v_mfma_f32_16x16x32_bf16 v[8:11], v[198:201], v[174:177], v[8:11]
	v_mfma_f32_16x16x32_bf16 v[4:7], v[190:193], v[182:185], v[4:7]
	s_setprio 0
	v_mfma_f32_16x16x32_bf16 v[0:3], v[198:201], v[182:185], v[0:3]
	s_barrier
; #define PG8_STAGE(bufoff, gbase, voff) do { _Pragma("unroll") for (int _i = 0; _i < 2; ++_i) \
;         __builtin_amdgcn_global_load_lds((const unsigned*)((const char*)(gbase) + (voff)[_i]), (LAS unsigned*)(lds + (bufoff) + ldsw + _i * 8192), 16, 0, 0); } while (0)
; #define PG8_LDA(dst, b, h) do { _Pragma("unroll") for (int m = 0; m < 4; ++m) _Pragma("unroll") for (int k = 0; k < 2; ++k) dst[m][k] = *(const LAS bf16x8*)(lds + PG8_SA(b, h) + aoff + m * 2048 + k * 1024); } while (0)
; #define PG8_LDB(dst, b, h) do { _Pragma("unroll") for (int n = 0; n < 2; ++n) _Pragma("unroll") for (int k = 0; k < 2; ++k) dst[n][k] = *(const LAS bf16x8*)(lds + PG8_SB(b, h) + boff + n * 2048 + k * 1024); } while (0)
; #define PG8_MMA(ai, bj, At, Bt) do { __builtin_amdgcn_s_setprio(1); _Pragma("unroll") for (int m = 0; m < 4; ++m) _Pragma("unroll") for (int n = 0; n < 2; ++n) _Pragma("unroll") for (int k = 0; k < 2; ++k) \
;         acc[ai][bj][m][n] = __builtin_amdgcn_mfma_f32_16x16x32_bf16(Bt[n][k], At[m][k], acc[ai][bj][m][n], 0, 0, 0); __builtin_amdgcn_s_setprio(0); } while (0)
; #define PG8_WAIT_V(n) asm volatile("s_waitcnt vmcnt(" #n ")" ::: "memory")
; #define PG8_WAIT_L(n) asm volatile("s_waitcnt lgkmcnt(" #n ")" ::: "memory")
; #define PG8_BAR __builtin_amdgcn_s_barrier()
; #define PG8_SCHED __builtin_amdgcn_sched_barrier(0)
; template <class Epi>
; __device__ __forceinline__ void gemm_phase(LAS unsigned char* lds, const Gemm g, const StaticOrder& S, const Epi& E) {
;     ...
;             PG8_LDB(B0, 1, 0); PG8_SCHED; PG8_LDA(At, 1, 0); PG8_STAGE(PG8_SA(0, 1), a2 + hstepA, voffA);
;             PG8_WAIT_L(8); PG8_BAR; PG8_WAIT_L(0); PG8_MMA(0, 0, At, B0); PG8_BAR; PG8_SCHED;
;             PG8_LDB(B1, 1, 1); PG8_STAGE(PG8_SB(1, 0), b3, voffB);
;             PG8_BAR; PG8_WAIT_L(0); PG8_MMA(0, 1, At, B1); PG8_BAR;
;             PG8_LDA(At, 1, 1); PG8_STAGE(PG8_SA(1, 0), a3, voffA);
;             PG8_BAR; PG8_WAIT_L(0); PG8_MMA(1, 0, At, B0); PG8_BAR; PG8_SCHED;
;             PG8_STAGE(PG8_SB(1, 1), b3 + hstepB, voffB);
;             PG8_WAIT_V(6); PG8_BAR; PG8_MMA(1, 1, At, B1); PG8_BAR;
	s_add_u32 s26, s26, s52
	s_addc_u32 s27, s27, 0
	s_mov_b32 m0, s35
	v_lshl_add_u64 v[186:187], s[26:27], 0, v[152:153]
	global_load_lds_dwordx4 v[186:187], off nt
	s_mov_b32 m0, s36
	v_lshl_add_u64 v[186:187], s[26:27], 0, v[156:157]
	global_load_lds_dwordx4 v[186:187], off nt
	ds_read_b128 v[128:131], v140
	ds_read_b128 v[136:139], v140 offset:2048
	ds_read_b128 v[132:135], v140 offset:1024
	ds_read_b128 v[140:143], v140 offset:3072
	ds_read_b128 v[144:147], v209 offset:32768
	ds_read_b128 v[162:165], v209 offset:34816
	ds_read_b128 v[170:173], v209 offset:36864
	ds_read_b128 v[178:181], v209 offset:38912
	ds_read_b128 v[148:151], v209 offset:33792
	ds_read_b128 v[166:169], v209 offset:35840
	ds_read_b128 v[174:177], v209 offset:37888
	ds_read_b128 v[182:185], v209 offset:39936
	s_mov_b32 s26, 0x1c000
	s_add_u32 s24, s24, 0x4000
	s_addc_u32 s25, s25, 0
	s_add_i32 s27, s55, s31
	v_add_u32_e32 v198, s26, v207
	ds_read_b128 v[186:189], v198
	ds_read_b128 v[194:197], v198 offset:2048
	ds_read_b128 v[190:193], v198 offset:1024
	ds_read_b128 v[198:201], v198 offset:3072
	s_waitcnt lgkmcnt(0)
	s_barrier
	v_mfma_f32_16x16x32_bf16 v[124:127], v[128:131], v[144:147], v[124:127]
	s_setprio 1
	v_mfma_f32_16x16x32_bf16 v[120:123], v[136:139], v[144:147], v[120:123]
	v_mfma_f32_16x16x32_bf16 v[116:119], v[128:131], v[162:165], v[116:119]
	v_mfma_f32_16x16x32_bf16 v[112:115], v[136:139], v[162:165], v[112:115]
	v_mfma_f32_16x16x32_bf16 v[108:111], v[128:131], v[170:173], v[108:111]
	v_mfma_f32_16x16x32_bf16 v[104:107], v[136:139], v[170:173], v[104:107]
	v_mfma_f32_16x16x32_bf16 v[100:103], v[128:131], v[178:181], v[100:103]
	v_mfma_f32_16x16x32_bf16 v[96:99], v[136:139], v[178:181], v[96:99]
	v_mfma_f32_16x16x32_bf16 v[124:127], v[132:135], v[148:151], v[124:127]
	v_mfma_f32_16x16x32_bf16 v[120:123], v[140:143], v[148:151], v[120:123]
	v_mfma_f32_16x16x32_bf16 v[116:119], v[132:135], v[166:169], v[116:119]
	v_mfma_f32_16x16x32_bf16 v[112:115], v[140:143], v[166:169], v[112:115]
	v_mfma_f32_16x16x32_bf16 v[108:111], v[132:135], v[174:177], v[108:111]
	v_mfma_f32_16x16x32_bf16 v[104:107], v[140:143], v[174:177], v[104:107]
	v_mfma_f32_16x16x32_bf16 v[100:103], v[132:135], v[182:185], v[100:103]
	v_mfma_f32_16x16x32_bf16 v[96:99], v[140:143], v[182:185], v[96:99]
	v_mfma_f32_16x16x32_bf16 v[92:95], v[186:189], v[144:147], v[92:95]
	v_mfma_f32_16x16x32_bf16 v[88:91], v[194:197], v[144:147], v[88:91]
	v_mfma_f32_16x16x32_bf16 v[84:87], v[186:189], v[162:165], v[84:87]
	v_mfma_f32_16x16x32_bf16 v[80:83], v[194:197], v[162:165], v[80:83]
	v_mfma_f32_16x16x32_bf16 v[76:79], v[186:189], v[170:173], v[76:79]
	v_mfma_f32_16x16x32_bf16 v[72:75], v[194:197], v[170:173], v[72:75]
	v_mfma_f32_16x16x32_bf16 v[68:71], v[186:189], v[178:181], v[68:71]
	v_mfma_f32_16x16x32_bf16 v[64:67], v[194:197], v[178:181], v[64:67]
	v_mfma_f32_16x16x32_bf16 v[92:95], v[190:193], v[148:151], v[92:95]
	v_mfma_f32_16x16x32_bf16 v[88:91], v[198:201], v[148:151], v[88:91]
	v_mfma_f32_16x16x32_bf16 v[84:87], v[190:193], v[166:169], v[84:87]
	v_mfma_f32_16x16x32_bf16 v[80:83], v[198:201], v[166:169], v[80:83]
	v_mfma_f32_16x16x32_bf16 v[76:79], v[190:193], v[174:177], v[76:79]
	v_mfma_f32_16x16x32_bf16 v[72:75], v[198:201], v[174:177], v[72:75]
	v_mfma_f32_16x16x32_bf16 v[68:71], v[190:193], v[182:185], v[68:71]
	s_setprio 0
	v_mfma_f32_16x16x32_bf16 v[64:67], v[198:201], v[182:185], v[64:67]
	s_barrier
	s_mov_b32 m0, s27
	v_lshl_add_u64 v[202:203], s[24:25], 0, v[152:153]
	global_load_lds_dwordx4 v[202:203], off
	s_add_i32 m0, s27, 0x2000
	v_lshl_add_u64 v[202:203], s[24:25], 0, v[156:157]
	global_load_lds_dwordx4 v[202:203], off
	s_mov_b32 m0, s38
	v_lshl_add_u64 v[202:203], s[22:23], 0, v[152:153]
	global_load_lds_dwordx4 v[202:203], off nt
	s_mov_b32 m0, s39
	v_lshl_add_u64 v[202:203], s[22:23], 0, v[156:157]
	global_load_lds_dwordx4 v[202:203], off nt
	s_add_u32 s22, s24, s52
	s_addc_u32 s23, s25, 0
	s_add_i32 s24, s26, s31
	s_mov_b32 m0, s24
	v_lshl_add_u64 v[202:203], s[22:23], 0, v[152:153]
	global_load_lds_dwordx4 v[202:203], off
	s_add_i32 m0, s24, 0x2000
	v_lshl_add_u64 v[202:203], s[22:23], 0, v[156:157]
	global_load_lds_dwordx4 v[202:203], off
	ds_read_b128 v[144:147], v209 offset:49152
	ds_read_b128 v[162:165], v209 offset:51200
	ds_read_b128 v[170:173], v209 offset:53248
	ds_read_b128 v[178:181], v209 offset:55296
	ds_read_b128 v[148:151], v209 offset:50176
	ds_read_b128 v[166:169], v209 offset:52224
	ds_read_b128 v[174:177], v209 offset:54272
	ds_read_b128 v[182:185], v209 offset:56320
	s_waitcnt vmcnt(6)
	s_waitcnt lgkmcnt(0)
	s_barrier
	v_mfma_f32_16x16x32_bf16 v[60:63], v[128:131], v[144:147], v[60:63]
	s_setprio 1
	v_mfma_f32_16x16x32_bf16 v[56:59], v[136:139], v[144:147], v[56:59]
	v_mfma_f32_16x16x32_bf16 v[52:55], v[128:131], v[162:165], v[52:55]
	v_mfma_f32_16x16x32_bf16 v[48:51], v[136:139], v[162:165], v[48:51]
	v_mfma_f32_16x16x32_bf16 v[44:47], v[128:131], v[170:173], v[44:47]
	v_mfma_f32_16x16x32_bf16 v[40:43], v[136:139], v[170:173], v[40:43]
	v_mfma_f32_16x16x32_bf16 v[36:39], v[128:131], v[178:181], v[36:39]
	v_mfma_f32_16x16x32_bf16 v[32:35], v[136:139], v[178:181], v[32:35]
	v_mfma_f32_16x16x32_bf16 v[60:63], v[132:135], v[148:151], v[60:63]
	v_mfma_f32_16x16x32_bf16 v[56:59], v[140:143], v[148:151], v[56:59]
	v_mfma_f32_16x16x32_bf16 v[52:55], v[132:135], v[166:169], v[52:55]
	v_mfma_f32_16x16x32_bf16 v[48:51], v[140:143], v[166:169], v[48:51]
	v_mfma_f32_16x16x32_bf16 v[44:47], v[132:135], v[174:177], v[44:47]
	v_mfma_f32_16x16x32_bf16 v[40:43], v[140:143], v[174:177], v[40:43]
	v_mfma_f32_16x16x32_bf16 v[36:39], v[132:135], v[182:185], v[36:39]
	v_mfma_f32_16x16x32_bf16 v[32:35], v[140:143], v[182:185], v[32:35]
	v_mfma_f32_16x16x32_bf16 v[28:31], v[186:189], v[144:147], v[28:31]
	v_mfma_f32_16x16x32_bf16 v[24:27], v[194:197], v[144:147], v[24:27]
	s_add_u32 s4, s4, 0x8000
	s_addc_u32 s5, s5, 0
	s_add_u32 s50, s50, 0x8000
	s_addc_u32 s51, s51, 0
	v_mfma_f32_16x16x32_bf16 v[20:23], v[186:189], v[162:165], v[20:23]
	v_mfma_f32_16x16x32_bf16 v[16:19], v[194:197], v[162:165], v[16:19]
	v_mfma_f32_16x16x32_bf16 v[12:15], v[186:189], v[170:173], v[12:15]
	v_mfma_f32_16x16x32_bf16 v[8:11], v[194:197], v[170:173], v[8:11]
	v_mfma_f32_16x16x32_bf16 v[4:7], v[186:189], v[178:181], v[4:7]
	v_mfma_f32_16x16x32_bf16 v[0:3], v[194:197], v[178:181], v[0:3]
	v_mfma_f32_16x16x32_bf16 v[28:31], v[190:193], v[148:151], v[28:31]
	v_mfma_f32_16x16x32_bf16 v[24:27], v[198:201], v[148:151], v[24:27]
	v_mfma_f32_16x16x32_bf16 v[20:23], v[190:193], v[166:169], v[20:23]
	v_mfma_f32_16x16x32_bf16 v[16:19], v[198:201], v[166:169], v[16:19]
	v_mfma_f32_16x16x32_bf16 v[12:15], v[190:193], v[174:177], v[12:15]
	v_mfma_f32_16x16x32_bf16 v[8:11], v[198:201], v[174:177], v[8:11]
	v_mfma_f32_16x16x32_bf16 v[4:7], v[190:193], v[182:185], v[4:7]
	s_cmp_ge_u32 s54, s28
	s_mov_b32 s22, s54
	s_setprio 0
	v_mfma_f32_16x16x32_bf16 v[0:3], v[198:201], v[182:185], v[0:3]
	s_barrier
	s_cbranch_scc0 .LBB0_187
